# x-projection GEMM main loop: one LDS-DMA load of the first and third load segments issued behind the MFMAs of the preceding compute segment of the same wave (3/4/3/4 + 1 + 1)
# baseline (speedup 1.0000x reference)
.LBB0_630:
	s_ashr_i32 s85, s84, 31
	s_lshl_b64 s[22:23], s[84:85], 20
	s_cmp_eq_u32 s52, 0
	v_mov_b64_e32 v[0:1], 0x3a0
	s_cselect_b32 s31, s14, s50
	v_cmp_lt_i64_e32 vcc, s[76:77], v[0:1]
	s_cselect_b32 s30, s15, s51
	s_cselect_b32 s38, s8, s14
	s_cselect_b32 s39, s9, s15
	s_add_u32 s76, s31, s22
	s_addc_u32 s77, s30, s23
	s_and_b64 s[22:23], vcc, exec
	s_cselect_b32 s30, s77, s89
	s_cselect_b32 s31, s76, s88
	s_ashr_i32 s83, s82, 31
	s_lshl_b64 s[22:23], s[82:83], 20
	s_add_u32 s86, s38, s22
	s_addc_u32 s87, s39, s23
	s_and_b64 s[22:23], vcc, exec
	s_cselect_b32 s38, s87, s91
	s_cselect_b32 s39, s86, s90
	s_add_u32 s88, s88, 0x80080
	s_addc_u32 s89, s89, 0
	s_add_u32 s41, s90, 0x100
	s_addc_u32 s42, s91, 0
	s_mov_b32 s43, -2
	s_add_u32 s22, s88, 0xfff80080
	s_addc_u32 s23, s89, -1
	s_add_u32 s44, s88, 0xfff80000
	s_addc_u32 s45, s89, -1
	s_cmp_eq_u32 s43, 28
	s_cselect_b32 s23, s30, s23
	s_cselect_b32 s22, s31, s22
	s_cselect_b32 s91, s38, s42
	s_cselect_b32 s90, s39, s41
	s_add_i32 s81, 0, 0x14000
	ds_read_b128 v[144:147], v222
	ds_read_b128 v[148:151], v222 offset:1024
	ds_read_b128 v[152:155], v222 offset:2048
	ds_read_b128 v[156:159], v222 offset:3072
	ds_read_b128 v[160:163], v223
	ds_read_b128 v[164:167], v223 offset:1024
	ds_read_b128 v[168:171], v223 offset:2048
	ds_read_b128 v[172:175], v223 offset:3072
	s_mov_b32 m0, s6
	ds_read_b128 v[176:179], v143
	ds_read_b128 v[180:183], v143 offset:1024
	ds_read_b128 v[184:187], v143 offset:2048
	ds_read_b128 v[188:191], v143 offset:3072
	ds_read_b128 v[192:195], v143 offset:4096
	ds_read_b128 v[196:199], v143 offset:5120
	ds_read_b128 v[200:203], v143 offset:6144
	ds_read_b128 v[204:207], v143 offset:7168
	global_load_lds_dwordx4 v132, s[44:45]
	s_add_i32 m0, s57, 0xc000
	s_nop 0
	global_load_lds_dwordx4 v136, s[88:89]
	s_add_i32 m0, s57, 0xe000
	s_nop 0
	global_load_lds_dwordx4 v138, s[88:89]
	s_waitcnt vmcnt(8)
	s_waitcnt lgkmcnt(0)
	s_barrier
	v_mfma_f32_16x16x32_bf16 v[124:127], v[144:147], v[176:179], 0
	v_mfma_f32_16x16x32_bf16 v[120:123], v[152:155], v[176:179], 0
	v_mfma_f32_16x16x32_bf16 v[116:119], v[144:147], v[184:187], 0
	v_mfma_f32_16x16x32_bf16 v[112:115], v[152:155], v[184:187], 0
	v_mfma_f32_16x16x32_bf16 v[100:103], v[144:147], v[192:195], 0
	v_mfma_f32_16x16x32_bf16 v[96:99], v[152:155], v[192:195], 0
	v_mfma_f32_16x16x32_bf16 v[84:87], v[144:147], v[200:203], 0
	v_mfma_f32_16x16x32_bf16 v[80:83], v[152:155], v[200:203], 0
	v_mfma_f32_16x16x32_bf16 v[124:127], v[148:151], v[180:183], v[124:127]
	v_mfma_f32_16x16x32_bf16 v[120:123], v[156:159], v[180:183], v[120:123]
	v_mfma_f32_16x16x32_bf16 v[116:119], v[148:151], v[188:191], v[116:119]
	v_mfma_f32_16x16x32_bf16 v[112:115], v[156:159], v[188:191], v[112:115]
	v_mfma_f32_16x16x32_bf16 v[100:103], v[148:151], v[196:199], v[100:103]
	v_mfma_f32_16x16x32_bf16 v[96:99], v[156:159], v[196:199], v[96:99]
	v_mfma_f32_16x16x32_bf16 v[84:87], v[148:151], v[204:207], v[84:87]
	v_mfma_f32_16x16x32_bf16 v[80:83], v[156:159], v[204:207], v[80:83]
	v_mfma_f32_16x16x32_bf16 v[108:111], v[160:163], v[176:179], 0
	v_mfma_f32_16x16x32_bf16 v[104:107], v[168:171], v[176:179], 0
	v_mfma_f32_16x16x32_bf16 v[92:95], v[160:163], v[184:187], 0
	v_mfma_f32_16x16x32_bf16 v[88:91], v[168:171], v[184:187], 0
	v_mfma_f32_16x16x32_bf16 v[76:79], v[160:163], v[192:195], 0
	v_mfma_f32_16x16x32_bf16 v[72:75], v[168:171], v[192:195], 0
	v_mfma_f32_16x16x32_bf16 v[68:71], v[160:163], v[200:203], 0
	v_mfma_f32_16x16x32_bf16 v[64:67], v[168:171], v[200:203], 0
	v_mfma_f32_16x16x32_bf16 v[108:111], v[164:167], v[180:183], v[108:111]
	v_mfma_f32_16x16x32_bf16 v[104:107], v[172:175], v[180:183], v[104:107]
	v_mfma_f32_16x16x32_bf16 v[92:95], v[164:167], v[188:191], v[92:95]
	v_mfma_f32_16x16x32_bf16 v[88:91], v[172:175], v[188:191], v[88:91]
	v_mfma_f32_16x16x32_bf16 v[76:79], v[164:167], v[196:199], v[76:79]
	v_mfma_f32_16x16x32_bf16 v[72:75], v[172:175], v[196:199], v[72:75]
	v_mfma_f32_16x16x32_bf16 v[68:71], v[164:167], v[204:207], v[68:71]
	v_mfma_f32_16x16x32_bf16 v[64:67], v[172:175], v[204:207], v[64:67]
	s_barrier
	s_add_i32 s44, s96, 0x10000
	s_mov_b32 m0, s44
	ds_read_b128 v[176:179], v143 offset:16384
	ds_read_b128 v[180:183], v143 offset:17408
	ds_read_b128 v[184:187], v143 offset:18432
	ds_read_b128 v[188:191], v143 offset:19456
	ds_read_b128 v[192:195], v143 offset:20480
	ds_read_b128 v[196:199], v143 offset:21504
	ds_read_b128 v[200:203], v143 offset:22528
	ds_read_b128 v[204:207], v143 offset:23552
	global_load_lds_dwordx4 v130, s[90:91]
	s_add_i32 m0, s44, 0x2000
	s_add_u32 s44, s90, 0x80000
	s_addc_u32 s45, s91, 0
	s_add_i32 s81, s81, s96
	global_load_lds_dwordx4 v134, s[90:91]
	s_mov_b32 m0, s81
	s_nop 0
	global_load_lds_dwordx4 v130, s[44:45]
	s_add_i32 m0, s81, 0x2000
	s_nop 0
	global_load_lds_dwordx4 v134, s[44:45]
	s_waitcnt vmcnt(6)
	s_waitcnt lgkmcnt(0)
	s_barrier
	v_mfma_f32_16x16x32_bf16 v[60:63], v[144:147], v[176:179], 0
	v_mfma_f32_16x16x32_bf16 v[56:59], v[152:155], v[176:179], 0
	v_mfma_f32_16x16x32_bf16 v[52:55], v[144:147], v[184:187], 0
	v_mfma_f32_16x16x32_bf16 v[48:51], v[152:155], v[184:187], 0
	v_mfma_f32_16x16x32_bf16 v[36:39], v[144:147], v[192:195], 0
	v_mfma_f32_16x16x32_bf16 v[32:35], v[152:155], v[192:195], 0
	v_mfma_f32_16x16x32_bf16 v[20:23], v[144:147], v[200:203], 0
	v_mfma_f32_16x16x32_bf16 v[16:19], v[152:155], v[200:203], 0
	v_mfma_f32_16x16x32_bf16 v[60:63], v[148:151], v[180:183], v[60:63]
	v_mfma_f32_16x16x32_bf16 v[56:59], v[156:159], v[180:183], v[56:59]
	v_mfma_f32_16x16x32_bf16 v[52:55], v[148:151], v[188:191], v[52:55]
	v_mfma_f32_16x16x32_bf16 v[48:51], v[156:159], v[188:191], v[48:51]
	v_mfma_f32_16x16x32_bf16 v[36:39], v[148:151], v[196:199], v[36:39]
	v_mfma_f32_16x16x32_bf16 v[32:35], v[156:159], v[196:199], v[32:35]
	v_mfma_f32_16x16x32_bf16 v[20:23], v[148:151], v[204:207], v[20:23]
	v_mfma_f32_16x16x32_bf16 v[16:19], v[156:159], v[204:207], v[16:19]
	v_mfma_f32_16x16x32_bf16 v[44:47], v[160:163], v[176:179], 0
	v_mfma_f32_16x16x32_bf16 v[40:43], v[168:171], v[176:179], 0
	v_mfma_f32_16x16x32_bf16 v[28:31], v[160:163], v[184:187], 0
	v_mfma_f32_16x16x32_bf16 v[24:27], v[168:171], v[184:187], 0
	v_mfma_f32_16x16x32_bf16 v[12:15], v[160:163], v[192:195], 0
	v_mfma_f32_16x16x32_bf16 v[8:11], v[168:171], v[192:195], 0
	v_mfma_f32_16x16x32_bf16 v[4:7], v[160:163], v[200:203], 0
	v_mfma_f32_16x16x32_bf16 v[0:3], v[168:171], v[200:203], 0
	v_mfma_f32_16x16x32_bf16 v[44:47], v[164:167], v[180:183], v[44:47]
	v_mfma_f32_16x16x32_bf16 v[40:43], v[172:175], v[180:183], v[40:43]
	v_mfma_f32_16x16x32_bf16 v[28:31], v[164:167], v[188:191], v[28:31]
	v_mfma_f32_16x16x32_bf16 v[24:27], v[172:175], v[188:191], v[24:27]
	v_mfma_f32_16x16x32_bf16 v[12:15], v[164:167], v[196:199], v[12:15]
	v_mfma_f32_16x16x32_bf16 v[8:11], v[172:175], v[196:199], v[8:11]
	v_mfma_f32_16x16x32_bf16 v[4:7], v[164:167], v[204:207], v[4:7]
	v_mfma_f32_16x16x32_bf16 v[0:3], v[172:175], v[204:207], v[0:3]
	s_mov_b32 m0, s57
	s_nop 0
	global_load_lds_dwordx4 v128, s[22:23]
	s_barrier
	s_add_i32 s44, 0, 0x18000
	s_add_i32 s45, 0, 0x1c000
	ds_read_b128 v[144:147], v224
	ds_read_b128 v[148:151], v224 offset:1024
	ds_read_b128 v[152:155], v224 offset:2048
	ds_read_b128 v[156:159], v224 offset:3072
	ds_read_b128 v[160:163], v225
	ds_read_b128 v[164:167], v225 offset:1024
	ds_read_b128 v[168:171], v225 offset:2048
	ds_read_b128 v[172:175], v225 offset:3072
	ds_read_b128 v[176:179], v143 offset:32768
	ds_read_b128 v[180:183], v143 offset:33792
	ds_read_b128 v[184:187], v143 offset:34816
	ds_read_b128 v[188:191], v143 offset:35840
	ds_read_b128 v[192:195], v143 offset:36864
	ds_read_b128 v[196:199], v143 offset:37888
	ds_read_b128 v[200:203], v143 offset:38912
	ds_read_b128 v[204:207], v143 offset:39936
	s_mov_b32 m0, s97
	s_nop 0
	global_load_lds_dwordx4 v132, s[22:23]
	s_mov_b32 m0, s93
	s_add_u32 s22, s22, 0x80000
	s_addc_u32 s23, s23, 0
	global_load_lds_dwordx4 v128, s[22:23]
	s_mov_b32 m0, s94
	s_nop 0
	global_load_lds_dwordx4 v132, s[22:23]
	s_waitcnt vmcnt(8)
	s_waitcnt lgkmcnt(0)
	s_barrier
	v_mfma_f32_16x16x32_bf16 v[124:127], v[144:147], v[176:179], v[124:127]
	v_mfma_f32_16x16x32_bf16 v[120:123], v[152:155], v[176:179], v[120:123]
	v_mfma_f32_16x16x32_bf16 v[116:119], v[144:147], v[184:187], v[116:119]
	v_mfma_f32_16x16x32_bf16 v[112:115], v[152:155], v[184:187], v[112:115]
	v_mfma_f32_16x16x32_bf16 v[100:103], v[144:147], v[192:195], v[100:103]
	v_mfma_f32_16x16x32_bf16 v[96:99], v[152:155], v[192:195], v[96:99]
	v_mfma_f32_16x16x32_bf16 v[84:87], v[144:147], v[200:203], v[84:87]
	v_mfma_f32_16x16x32_bf16 v[80:83], v[152:155], v[200:203], v[80:83]
	v_mfma_f32_16x16x32_bf16 v[124:127], v[148:151], v[180:183], v[124:127]
	v_mfma_f32_16x16x32_bf16 v[120:123], v[156:159], v[180:183], v[120:123]
	v_mfma_f32_16x16x32_bf16 v[116:119], v[148:151], v[188:191], v[116:119]
	v_mfma_f32_16x16x32_bf16 v[112:115], v[156:159], v[188:191], v[112:115]
	v_mfma_f32_16x16x32_bf16 v[100:103], v[148:151], v[196:199], v[100:103]
	v_mfma_f32_16x16x32_bf16 v[96:99], v[156:159], v[196:199], v[96:99]
	v_mfma_f32_16x16x32_bf16 v[84:87], v[148:151], v[204:207], v[84:87]
	v_mfma_f32_16x16x32_bf16 v[80:83], v[156:159], v[204:207], v[80:83]
	v_mfma_f32_16x16x32_bf16 v[108:111], v[160:163], v[176:179], v[108:111]
	v_mfma_f32_16x16x32_bf16 v[104:107], v[168:171], v[176:179], v[104:107]
	v_mfma_f32_16x16x32_bf16 v[92:95], v[160:163], v[184:187], v[92:95]
	v_mfma_f32_16x16x32_bf16 v[88:91], v[168:171], v[184:187], v[88:91]
	v_mfma_f32_16x16x32_bf16 v[76:79], v[160:163], v[192:195], v[76:79]
	v_mfma_f32_16x16x32_bf16 v[72:75], v[168:171], v[192:195], v[72:75]
	v_mfma_f32_16x16x32_bf16 v[68:71], v[160:163], v[200:203], v[68:71]
	v_mfma_f32_16x16x32_bf16 v[64:67], v[168:171], v[200:203], v[64:67]
	v_mfma_f32_16x16x32_bf16 v[108:111], v[164:167], v[180:183], v[108:111]
	v_mfma_f32_16x16x32_bf16 v[104:107], v[172:175], v[180:183], v[104:107]
	v_mfma_f32_16x16x32_bf16 v[92:95], v[164:167], v[188:191], v[92:95]
	v_mfma_f32_16x16x32_bf16 v[88:91], v[172:175], v[188:191], v[88:91]
	v_mfma_f32_16x16x32_bf16 v[76:79], v[164:167], v[196:199], v[76:79]
	v_mfma_f32_16x16x32_bf16 v[72:75], v[172:175], v[196:199], v[72:75]
	v_mfma_f32_16x16x32_bf16 v[68:71], v[164:167], v[204:207], v[68:71]
	v_mfma_f32_16x16x32_bf16 v[64:67], v[172:175], v[204:207], v[64:67]
	s_barrier
	s_add_i32 s22, s44, s96
	s_add_i32 m0, s22, 0xffffff80
	ds_read_b128 v[176:179], v143 offset:49152
	ds_read_b128 v[180:183], v143 offset:50176
	ds_read_b128 v[184:187], v143 offset:51200
	ds_read_b128 v[188:191], v143 offset:52224
	ds_read_b128 v[192:195], v143 offset:53248
	ds_read_b128 v[196:199], v143 offset:54272
	ds_read_b128 v[200:203], v143 offset:55296
	ds_read_b128 v[204:207], v143 offset:56320
	global_load_lds_dwordx4 v130, s[90:91] offset:128
	s_add_i32 m0, s22, 0x1f80
	s_add_u32 s22, s90, 0x80080
	s_addc_u32 s23, s91, 0
	s_add_i32 s44, s45, s96
	global_load_lds_dwordx4 v134, s[90:91] offset:128
	s_mov_b32 m0, s44
	s_nop 0
	global_load_lds_dwordx4 v130, s[22:23]
	s_add_i32 m0, s44, 0x2000
	s_nop 0
	global_load_lds_dwordx4 v134, s[22:23]
	s_waitcnt vmcnt(6)
	s_waitcnt lgkmcnt(0)
	s_barrier
	v_mfma_f32_16x16x32_bf16 v[60:63], v[144:147], v[176:179], v[60:63]
	v_mfma_f32_16x16x32_bf16 v[56:59], v[152:155], v[176:179], v[56:59]
	v_mfma_f32_16x16x32_bf16 v[52:55], v[144:147], v[184:187], v[52:55]
	v_mfma_f32_16x16x32_bf16 v[48:51], v[152:155], v[184:187], v[48:51]
	v_mfma_f32_16x16x32_bf16 v[36:39], v[144:147], v[192:195], v[36:39]
	v_mfma_f32_16x16x32_bf16 v[32:35], v[152:155], v[192:195], v[32:35]
	v_mfma_f32_16x16x32_bf16 v[20:23], v[144:147], v[200:203], v[20:23]
	v_mfma_f32_16x16x32_bf16 v[16:19], v[152:155], v[200:203], v[16:19]
	v_mfma_f32_16x16x32_bf16 v[60:63], v[148:151], v[180:183], v[60:63]
	v_mfma_f32_16x16x32_bf16 v[56:59], v[156:159], v[180:183], v[56:59]
	v_mfma_f32_16x16x32_bf16 v[52:55], v[148:151], v[188:191], v[52:55]
	v_mfma_f32_16x16x32_bf16 v[48:51], v[156:159], v[188:191], v[48:51]
	v_mfma_f32_16x16x32_bf16 v[36:39], v[148:151], v[196:199], v[36:39]
	v_mfma_f32_16x16x32_bf16 v[32:35], v[156:159], v[196:199], v[32:35]
	v_mfma_f32_16x16x32_bf16 v[20:23], v[148:151], v[204:207], v[20:23]
	v_mfma_f32_16x16x32_bf16 v[16:19], v[156:159], v[204:207], v[16:19]
	v_mfma_f32_16x16x32_bf16 v[44:47], v[160:163], v[176:179], v[44:47]
	v_mfma_f32_16x16x32_bf16 v[40:43], v[168:171], v[176:179], v[40:43]
	v_mfma_f32_16x16x32_bf16 v[28:31], v[160:163], v[184:187], v[28:31]
	v_mfma_f32_16x16x32_bf16 v[24:27], v[168:171], v[184:187], v[24:27]
	v_mfma_f32_16x16x32_bf16 v[12:15], v[160:163], v[192:195], v[12:15]
	v_mfma_f32_16x16x32_bf16 v[8:11], v[168:171], v[192:195], v[8:11]
	v_mfma_f32_16x16x32_bf16 v[4:7], v[160:163], v[200:203], v[4:7]
	v_mfma_f32_16x16x32_bf16 v[0:3], v[168:171], v[200:203], v[0:3]
	v_mfma_f32_16x16x32_bf16 v[44:47], v[164:167], v[180:183], v[44:47]
	v_mfma_f32_16x16x32_bf16 v[40:43], v[172:175], v[180:183], v[40:43]
	v_mfma_f32_16x16x32_bf16 v[28:31], v[164:167], v[188:191], v[28:31]
	v_mfma_f32_16x16x32_bf16 v[24:27], v[172:175], v[188:191], v[24:27]
	v_mfma_f32_16x16x32_bf16 v[12:15], v[164:167], v[196:199], v[12:15]
	v_mfma_f32_16x16x32_bf16 v[8:11], v[172:175], v[196:199], v[8:11]
	v_mfma_f32_16x16x32_bf16 v[4:7], v[164:167], v[204:207], v[4:7]
	v_mfma_f32_16x16x32_bf16 v[0:3], v[172:175], v[204:207], v[0:3]
	s_add_u32 s22, s88, 0xfff80080
	s_addc_u32 s23, s89, -1
	s_cmp_eq_u32 s43, 28
	s_cselect_b32 s23, s30, s23
	s_cselect_b32 s22, s31, s22
	s_add_i32 m0, s92, 0xffffff80
	s_nop 0
	global_load_lds_dwordx4 v128, s[22:23] offset:128
	s_barrier
	s_add_i32 s43, s43, 2
	s_add_u32 s88, s88, 0x100
	s_addc_u32 s89, s89, 0
	s_add_u32 s41, s41, 0x100
	s_addc_u32 s42, s42, 0
	s_cmp_gt_u32 s43, 29
	s_cbranch_scc0 .LBB0_631
.LBB0_631:
	s_add_u32 s22, s88, 0xfff80080
	s_addc_u32 s23, s89, -1
	s_add_u32 s44, s88, 0xfff80000
	s_addc_u32 s45, s89, -1
	s_cmp_eq_u32 s43, 28
	s_cselect_b32 s23, s30, s23
	s_cselect_b32 s22, s31, s22
	s_cselect_b32 s91, s38, s42
	s_cselect_b32 s90, s39, s41
	s_add_i32 s81, 0, 0x14000
	ds_read_b128 v[144:147], v222
	ds_read_b128 v[148:151], v222 offset:1024
	ds_read_b128 v[152:155], v222 offset:2048
	ds_read_b128 v[156:159], v222 offset:3072
	ds_read_b128 v[160:163], v223
	ds_read_b128 v[164:167], v223 offset:1024
	ds_read_b128 v[168:171], v223 offset:2048
	ds_read_b128 v[172:175], v223 offset:3072
	s_mov_b32 m0, s6
	ds_read_b128 v[176:179], v143
	ds_read_b128 v[180:183], v143 offset:1024
	ds_read_b128 v[184:187], v143 offset:2048
	ds_read_b128 v[188:191], v143 offset:3072
	ds_read_b128 v[192:195], v143 offset:4096
	ds_read_b128 v[196:199], v143 offset:5120
	ds_read_b128 v[200:203], v143 offset:6144
	ds_read_b128 v[204:207], v143 offset:7168
	global_load_lds_dwordx4 v132, s[44:45]
	s_add_i32 m0, s57, 0xc000
	s_nop 0
	global_load_lds_dwordx4 v136, s[88:89]
	s_add_i32 m0, s57, 0xe000
	s_nop 0
	global_load_lds_dwordx4 v138, s[88:89]
	s_waitcnt vmcnt(8)
	s_waitcnt lgkmcnt(0)
	s_barrier
	v_mfma_f32_16x16x32_bf16 v[124:127], v[144:147], v[176:179], v[124:127]
	v_mfma_f32_16x16x32_bf16 v[120:123], v[152:155], v[176:179], v[120:123]
	v_mfma_f32_16x16x32_bf16 v[116:119], v[144:147], v[184:187], v[116:119]
	v_mfma_f32_16x16x32_bf16 v[112:115], v[152:155], v[184:187], v[112:115]
	v_mfma_f32_16x16x32_bf16 v[100:103], v[144:147], v[192:195], v[100:103]
	v_mfma_f32_16x16x32_bf16 v[96:99], v[152:155], v[192:195], v[96:99]
	v_mfma_f32_16x16x32_bf16 v[84:87], v[144:147], v[200:203], v[84:87]
	v_mfma_f32_16x16x32_bf16 v[80:83], v[152:155], v[200:203], v[80:83]
	v_mfma_f32_16x16x32_bf16 v[124:127], v[148:151], v[180:183], v[124:127]
	v_mfma_f32_16x16x32_bf16 v[120:123], v[156:159], v[180:183], v[120:123]
	v_mfma_f32_16x16x32_bf16 v[116:119], v[148:151], v[188:191], v[116:119]
	v_mfma_f32_16x16x32_bf16 v[112:115], v[156:159], v[188:191], v[112:115]
	v_mfma_f32_16x16x32_bf16 v[100:103], v[148:151], v[196:199], v[100:103]
	v_mfma_f32_16x16x32_bf16 v[96:99], v[156:159], v[196:199], v[96:99]
	v_mfma_f32_16x16x32_bf16 v[84:87], v[148:151], v[204:207], v[84:87]
	v_mfma_f32_16x16x32_bf16 v[80:83], v[156:159], v[204:207], v[80:83]
	v_mfma_f32_16x16x32_bf16 v[108:111], v[160:163], v[176:179], v[108:111]
	v_mfma_f32_16x16x32_bf16 v[104:107], v[168:171], v[176:179], v[104:107]
	v_mfma_f32_16x16x32_bf16 v[92:95], v[160:163], v[184:187], v[92:95]
	v_mfma_f32_16x16x32_bf16 v[88:91], v[168:171], v[184:187], v[88:91]
	v_mfma_f32_16x16x32_bf16 v[76:79], v[160:163], v[192:195], v[76:79]
	v_mfma_f32_16x16x32_bf16 v[72:75], v[168:171], v[192:195], v[72:75]
	v_mfma_f32_16x16x32_bf16 v[68:71], v[160:163], v[200:203], v[68:71]
	v_mfma_f32_16x16x32_bf16 v[64:67], v[168:171], v[200:203], v[64:67]
	v_mfma_f32_16x16x32_bf16 v[108:111], v[164:167], v[180:183], v[108:111]
	v_mfma_f32_16x16x32_bf16 v[104:107], v[172:175], v[180:183], v[104:107]
	v_mfma_f32_16x16x32_bf16 v[92:95], v[164:167], v[188:191], v[92:95]
	v_mfma_f32_16x16x32_bf16 v[88:91], v[172:175], v[188:191], v[88:91]
	v_mfma_f32_16x16x32_bf16 v[76:79], v[164:167], v[196:199], v[76:79]
	v_mfma_f32_16x16x32_bf16 v[72:75], v[172:175], v[196:199], v[72:75]
	v_mfma_f32_16x16x32_bf16 v[68:71], v[164:167], v[204:207], v[68:71]
	v_mfma_f32_16x16x32_bf16 v[64:67], v[172:175], v[204:207], v[64:67]
	s_barrier
	s_add_i32 s44, s96, 0x10000
	s_mov_b32 m0, s44
	ds_read_b128 v[176:179], v143 offset:16384
	ds_read_b128 v[180:183], v143 offset:17408
	ds_read_b128 v[184:187], v143 offset:18432
	ds_read_b128 v[188:191], v143 offset:19456
	ds_read_b128 v[192:195], v143 offset:20480
	ds_read_b128 v[196:199], v143 offset:21504
	ds_read_b128 v[200:203], v143 offset:22528
	ds_read_b128 v[204:207], v143 offset:23552
	global_load_lds_dwordx4 v130, s[90:91]
	s_add_i32 m0, s44, 0x2000
	s_add_u32 s44, s90, 0x80000
	s_addc_u32 s45, s91, 0
	s_add_i32 s81, s81, s96
	global_load_lds_dwordx4 v134, s[90:91]
	s_mov_b32 m0, s81
	s_nop 0
	global_load_lds_dwordx4 v130, s[44:45]
	s_add_i32 m0, s81, 0x2000
	s_nop 0
	global_load_lds_dwordx4 v134, s[44:45]
	s_waitcnt vmcnt(6)
	s_waitcnt lgkmcnt(0)
	s_barrier
	v_mfma_f32_16x16x32_bf16 v[60:63], v[144:147], v[176:179], v[60:63]
	v_mfma_f32_16x16x32_bf16 v[56:59], v[152:155], v[176:179], v[56:59]
	v_mfma_f32_16x16x32_bf16 v[52:55], v[144:147], v[184:187], v[52:55]
	v_mfma_f32_16x16x32_bf16 v[48:51], v[152:155], v[184:187], v[48:51]
	v_mfma_f32_16x16x32_bf16 v[36:39], v[144:147], v[192:195], v[36:39]
	v_mfma_f32_16x16x32_bf16 v[32:35], v[152:155], v[192:195], v[32:35]
	v_mfma_f32_16x16x32_bf16 v[20:23], v[144:147], v[200:203], v[20:23]
	v_mfma_f32_16x16x32_bf16 v[16:19], v[152:155], v[200:203], v[16:19]
	v_mfma_f32_16x16x32_bf16 v[60:63], v[148:151], v[180:183], v[60:63]
	v_mfma_f32_16x16x32_bf16 v[56:59], v[156:159], v[180:183], v[56:59]
	v_mfma_f32_16x16x32_bf16 v[52:55], v[148:151], v[188:191], v[52:55]
	v_mfma_f32_16x16x32_bf16 v[48:51], v[156:159], v[188:191], v[48:51]
	v_mfma_f32_16x16x32_bf16 v[36:39], v[148:151], v[196:199], v[36:39]
	v_mfma_f32_16x16x32_bf16 v[32:35], v[156:159], v[196:199], v[32:35]
	v_mfma_f32_16x16x32_bf16 v[20:23], v[148:151], v[204:207], v[20:23]
	v_mfma_f32_16x16x32_bf16 v[16:19], v[156:159], v[204:207], v[16:19]
	v_mfma_f32_16x16x32_bf16 v[44:47], v[160:163], v[176:179], v[44:47]
	v_mfma_f32_16x16x32_bf16 v[40:43], v[168:171], v[176:179], v[40:43]
	v_mfma_f32_16x16x32_bf16 v[28:31], v[160:163], v[184:187], v[28:31]
	v_mfma_f32_16x16x32_bf16 v[24:27], v[168:171], v[184:187], v[24:27]
	v_mfma_f32_16x16x32_bf16 v[12:15], v[160:163], v[192:195], v[12:15]
	v_mfma_f32_16x16x32_bf16 v[8:11], v[168:171], v[192:195], v[8:11]
	v_mfma_f32_16x16x32_bf16 v[4:7], v[160:163], v[200:203], v[4:7]
	v_mfma_f32_16x16x32_bf16 v[0:3], v[168:171], v[200:203], v[0:3]
	v_mfma_f32_16x16x32_bf16 v[44:47], v[164:167], v[180:183], v[44:47]
	v_mfma_f32_16x16x32_bf16 v[40:43], v[172:175], v[180:183], v[40:43]
	v_mfma_f32_16x16x32_bf16 v[28:31], v[164:167], v[188:191], v[28:31]
	v_mfma_f32_16x16x32_bf16 v[24:27], v[172:175], v[188:191], v[24:27]
	v_mfma_f32_16x16x32_bf16 v[12:15], v[164:167], v[196:199], v[12:15]
	v_mfma_f32_16x16x32_bf16 v[8:11], v[172:175], v[196:199], v[8:11]
	v_mfma_f32_16x16x32_bf16 v[4:7], v[164:167], v[204:207], v[4:7]
	v_mfma_f32_16x16x32_bf16 v[0:3], v[172:175], v[204:207], v[0:3]
	s_mov_b32 m0, s57
	s_nop 0
	global_load_lds_dwordx4 v128, s[22:23]
	s_barrier
	s_add_i32 s44, 0, 0x18000
	s_add_i32 s45, 0, 0x1c000
	ds_read_b128 v[144:147], v224
	ds_read_b128 v[148:151], v224 offset:1024
	ds_read_b128 v[152:155], v224 offset:2048
	ds_read_b128 v[156:159], v224 offset:3072
	ds_read_b128 v[160:163], v225
	ds_read_b128 v[164:167], v225 offset:1024
	ds_read_b128 v[168:171], v225 offset:2048
	ds_read_b128 v[172:175], v225 offset:3072
	ds_read_b128 v[176:179], v143 offset:32768
	ds_read_b128 v[180:183], v143 offset:33792
	ds_read_b128 v[184:187], v143 offset:34816
	ds_read_b128 v[188:191], v143 offset:35840
	ds_read_b128 v[192:195], v143 offset:36864
	ds_read_b128 v[196:199], v143 offset:37888
	ds_read_b128 v[200:203], v143 offset:38912
	ds_read_b128 v[204:207], v143 offset:39936
	s_mov_b32 m0, s97
	s_nop 0
	global_load_lds_dwordx4 v132, s[22:23]
	s_mov_b32 m0, s93
	s_add_u32 s22, s22, 0x80000
	s_addc_u32 s23, s23, 0
	global_load_lds_dwordx4 v128, s[22:23]
	s_mov_b32 m0, s94
	s_nop 0
	global_load_lds_dwordx4 v132, s[22:23]
	s_waitcnt vmcnt(8)
	s_waitcnt lgkmcnt(0)
	s_barrier
	v_mfma_f32_16x16x32_bf16 v[124:127], v[144:147], v[176:179], v[124:127]
	v_mfma_f32_16x16x32_bf16 v[120:123], v[152:155], v[176:179], v[120:123]
	v_mfma_f32_16x16x32_bf16 v[116:119], v[144:147], v[184:187], v[116:119]
	v_mfma_f32_16x16x32_bf16 v[112:115], v[152:155], v[184:187], v[112:115]
	v_mfma_f32_16x16x32_bf16 v[100:103], v[144:147], v[192:195], v[100:103]
	v_mfma_f32_16x16x32_bf16 v[96:99], v[152:155], v[192:195], v[96:99]
	v_mfma_f32_16x16x32_bf16 v[84:87], v[144:147], v[200:203], v[84:87]
	v_mfma_f32_16x16x32_bf16 v[80:83], v[152:155], v[200:203], v[80:83]
	v_mfma_f32_16x16x32_bf16 v[124:127], v[148:151], v[180:183], v[124:127]
	v_mfma_f32_16x16x32_bf16 v[120:123], v[156:159], v[180:183], v[120:123]
	v_mfma_f32_16x16x32_bf16 v[116:119], v[148:151], v[188:191], v[116:119]
	v_mfma_f32_16x16x32_bf16 v[112:115], v[156:159], v[188:191], v[112:115]
	v_mfma_f32_16x16x32_bf16 v[100:103], v[148:151], v[196:199], v[100:103]
	v_mfma_f32_16x16x32_bf16 v[96:99], v[156:159], v[196:199], v[96:99]
	v_mfma_f32_16x16x32_bf16 v[84:87], v[148:151], v[204:207], v[84:87]
	v_mfma_f32_16x16x32_bf16 v[80:83], v[156:159], v[204:207], v[80:83]
	v_mfma_f32_16x16x32_bf16 v[108:111], v[160:163], v[176:179], v[108:111]
	v_mfma_f32_16x16x32_bf16 v[104:107], v[168:171], v[176:179], v[104:107]
	v_mfma_f32_16x16x32_bf16 v[92:95], v[160:163], v[184:187], v[92:95]
	v_mfma_f32_16x16x32_bf16 v[88:91], v[168:171], v[184:187], v[88:91]
	v_mfma_f32_16x16x32_bf16 v[76:79], v[160:163], v[192:195], v[76:79]
	v_mfma_f32_16x16x32_bf16 v[72:75], v[168:171], v[192:195], v[72:75]
	v_mfma_f32_16x16x32_bf16 v[68:71], v[160:163], v[200:203], v[68:71]
	v_mfma_f32_16x16x32_bf16 v[64:67], v[168:171], v[200:203], v[64:67]
	v_mfma_f32_16x16x32_bf16 v[108:111], v[164:167], v[180:183], v[108:111]
	v_mfma_f32_16x16x32_bf16 v[104:107], v[172:175], v[180:183], v[104:107]
	v_mfma_f32_16x16x32_bf16 v[92:95], v[164:167], v[188:191], v[92:95]
	v_mfma_f32_16x16x32_bf16 v[88:91], v[172:175], v[188:191], v[88:91]
	v_mfma_f32_16x16x32_bf16 v[76:79], v[164:167], v[196:199], v[76:79]
	v_mfma_f32_16x16x32_bf16 v[72:75], v[172:175], v[196:199], v[72:75]
	v_mfma_f32_16x16x32_bf16 v[68:71], v[164:167], v[204:207], v[68:71]
	v_mfma_f32_16x16x32_bf16 v[64:67], v[172:175], v[204:207], v[64:67]
	s_barrier
	s_add_i32 s22, s44, s96
	s_add_i32 m0, s22, 0xffffff80
	ds_read_b128 v[176:179], v143 offset:49152
	ds_read_b128 v[180:183], v143 offset:50176
	ds_read_b128 v[184:187], v143 offset:51200
	ds_read_b128 v[188:191], v143 offset:52224
	ds_read_b128 v[192:195], v143 offset:53248
	ds_read_b128 v[196:199], v143 offset:54272
	ds_read_b128 v[200:203], v143 offset:55296
	ds_read_b128 v[204:207], v143 offset:56320
	global_load_lds_dwordx4 v130, s[90:91] offset:128
	s_add_i32 m0, s22, 0x1f80
	s_add_u32 s22, s90, 0x80080
	s_addc_u32 s23, s91, 0
	s_add_i32 s44, s45, s96
	global_load_lds_dwordx4 v134, s[90:91] offset:128
	s_mov_b32 m0, s44
	s_nop 0
	global_load_lds_dwordx4 v130, s[22:23]
	s_add_i32 m0, s44, 0x2000
	s_nop 0
	global_load_lds_dwordx4 v134, s[22:23]
	s_waitcnt vmcnt(6)
	s_waitcnt lgkmcnt(0)
	s_barrier
	v_mfma_f32_16x16x32_bf16 v[60:63], v[144:147], v[176:179], v[60:63]
	v_mfma_f32_16x16x32_bf16 v[56:59], v[152:155], v[176:179], v[56:59]
	v_mfma_f32_16x16x32_bf16 v[52:55], v[144:147], v[184:187], v[52:55]
	v_mfma_f32_16x16x32_bf16 v[48:51], v[152:155], v[184:187], v[48:51]
	v_mfma_f32_16x16x32_bf16 v[36:39], v[144:147], v[192:195], v[36:39]
	v_mfma_f32_16x16x32_bf16 v[32:35], v[152:155], v[192:195], v[32:35]
	v_mfma_f32_16x16x32_bf16 v[20:23], v[144:147], v[200:203], v[20:23]
	v_mfma_f32_16x16x32_bf16 v[16:19], v[152:155], v[200:203], v[16:19]
	v_mfma_f32_16x16x32_bf16 v[60:63], v[148:151], v[180:183], v[60:63]
	v_mfma_f32_16x16x32_bf16 v[56:59], v[156:159], v[180:183], v[56:59]
	v_mfma_f32_16x16x32_bf16 v[52:55], v[148:151], v[188:191], v[52:55]
	v_mfma_f32_16x16x32_bf16 v[48:51], v[156:159], v[188:191], v[48:51]
	v_mfma_f32_16x16x32_bf16 v[36:39], v[148:151], v[196:199], v[36:39]
	v_mfma_f32_16x16x32_bf16 v[32:35], v[156:159], v[196:199], v[32:35]
	v_mfma_f32_16x16x32_bf16 v[20:23], v[148:151], v[204:207], v[20:23]
	v_mfma_f32_16x16x32_bf16 v[16:19], v[156:159], v[204:207], v[16:19]
	v_mfma_f32_16x16x32_bf16 v[44:47], v[160:163], v[176:179], v[44:47]
	v_mfma_f32_16x16x32_bf16 v[40:43], v[168:171], v[176:179], v[40:43]
	v_mfma_f32_16x16x32_bf16 v[28:31], v[160:163], v[184:187], v[28:31]
	v_mfma_f32_16x16x32_bf16 v[24:27], v[168:171], v[184:187], v[24:27]
	v_mfma_f32_16x16x32_bf16 v[12:15], v[160:163], v[192:195], v[12:15]
	v_mfma_f32_16x16x32_bf16 v[8:11], v[168:171], v[192:195], v[8:11]
	v_mfma_f32_16x16x32_bf16 v[4:7], v[160:163], v[200:203], v[4:7]
	v_mfma_f32_16x16x32_bf16 v[0:3], v[168:171], v[200:203], v[0:3]
	v_mfma_f32_16x16x32_bf16 v[44:47], v[164:167], v[180:183], v[44:47]
	v_mfma_f32_16x16x32_bf16 v[40:43], v[172:175], v[180:183], v[40:43]
	v_mfma_f32_16x16x32_bf16 v[28:31], v[164:167], v[188:191], v[28:31]
	v_mfma_f32_16x16x32_bf16 v[24:27], v[172:175], v[188:191], v[24:27]
	v_mfma_f32_16x16x32_bf16 v[12:15], v[164:167], v[196:199], v[12:15]
	v_mfma_f32_16x16x32_bf16 v[8:11], v[172:175], v[196:199], v[8:11]
	v_mfma_f32_16x16x32_bf16 v[4:7], v[164:167], v[204:207], v[4:7]
	v_mfma_f32_16x16x32_bf16 v[0:3], v[172:175], v[204:207], v[0:3]
	s_add_u32 s22, s88, 0xfff80080
	s_addc_u32 s23, s89, -1
	s_cmp_eq_u32 s43, 28
	s_cselect_b32 s23, s30, s23
	s_cselect_b32 s22, s31, s22
	s_add_i32 m0, s92, 0xffffff80
	s_nop 0
	global_load_lds_dwordx4 v128, s[22:23] offset:128
	s_barrier
	s_add_i32 s43, s43, 2
	s_add_u32 s88, s88, 0x100
	s_addc_u32 s89, s89, 0
	s_add_u32 s41, s41, 0x100
	s_addc_u32 s42, s42, 0
	s_cmp_gt_u32 s43, 29
	s_cbranch_scc0 .LBB0_631
	s_cmp_eq_u32 s40, 0
	s_cselect_b64 s[30:31], -1, 0
	s_cmp_lg_u32 s40, 0
	s_mov_b64 s[38:39], -1
	s_cbranch_scc0 .LBB0_634
	s_lshl_b32 s22, s80, 8
	s_or_b32 s22, s22, s53
	s_ashr_i32 s22, s22, 6
	s_mov_b64 s[38:39], 0
